# attention: K-fragment ds_reads issued ahead of the global prefetch loads after each tile barrier; s_setprio 1 around the MFMA-only bursts (S0=QK block 0, PV block 1)
# speedup vs baseline: 1.0079x; 1.0048x over previous
; #define LAS __attribute__((address_space(3)))
; template <int MODE> __device__ __forceinline__ void attn_phase(LAS unsigned char* lds, const bf16_t* Q, const bf16_t* KF, const bf16_t* VT, bf16_t* O, const int* positions, const float* gq, int G, int bid) {
;     ...
;             for (int kt = 0; kt < ntiles; ++kt) {
;                 const bool more = (kt + 1 < ntiles);
;                 if (more && MODE < 3) { AT_GLOAD_K(kt + 1); AT_GLOAD_V(kt + 1); }
;                 if (kt <= my_last) {
;                     LAS unsigned char* kb = lds + (kt & 1) * AT_STAGE; LAS unsigned char* vb = kb + AT_KBYTES;
;     ...
;                     f32x16 s0, s1;
; #pragma unroll
;                     for (int i = 0; i < 16; ++i) s0[i] = -mrun;
;                     bf16x8 fr[8], fr2[4];
; #pragma unroll
;                     for (int kk = 0; kk < 8; ++kk) fr[kk] = *(const LAS bf16x8*)(kb + lq * AT_KP + (16 * kk + 8 * hi) * 2);
;                     __builtin_amdgcn_sched_barrier(0);
; #pragma unroll
;                     for (int kk = 0; kk < 4; ++kk) s0 = __builtin_amdgcn_mfma_f32_32x32x16_bf16(fr[kk], qf[kk], s0, 0, 0, 0);
;                     __builtin_amdgcn_sched_barrier(0);
; #pragma unroll
;                     for (int kk = 8; kk < 12; ++kk) fr2[kk - 8] = *(const LAS bf16x8*)(kb + lq * AT_KP + (16 * kk + 8 * hi) * 2);
;                     __builtin_amdgcn_sched_barrier(0);
; #pragma unroll
;                     for (int kk = 4; kk < 8; ++kk) s0 = __builtin_amdgcn_mfma_f32_32x32x16_bf16(fr[kk], qf[kk], s0, 0, 0, 0);
; #pragma unroll
;                     for (int kk = 8; kk < 12; ++kk) s0 = __builtin_amdgcn_mfma_f32_32x32x16_bf16(fr2[kk - 8], qf[kk], s0, 0, 0, 0);
;                     __builtin_amdgcn_sched_barrier(0);
; #pragma unroll
;                     for (int kk = 0; kk < 8; ++kk) fr[kk] = *(const LAS bf16x8*)(kb + (32 + lq) * AT_KP + (16 * kk + 8 * hi) * 2);
;                     __builtin_amdgcn_sched_barrier(0);
;                     float mx = fmaxf(fmaxf(s0[0], s0[1]), fmaxf(s0[2], s0[3]));
; #pragma unroll
;                     for (int i = 4; i < 16; i += 2) mx = fmaxf(mx, fmaxf(s0[i], s0[i + 1]));
;                     mx = fmaxf(mx, __shfl_xor(mx, 32));
;                     if (__any(mx > 6.0f)) AT_RESCALE(_Pragma("unroll") for (int i = 0; i < 16; ++i) s0[i] -= d_;);
.LBB0_668:
	s_add_i32 s7, s22, 1
	v_cmp_gt_i32_e64 s[10:11], s22, v244
	v_cmp_le_i32_e32 vcc, s22, v244
	s_cbranch_vccz .Lattn_idle
	s_and_saveexec_b64 s[44:45], vcc
	s_cbranch_execz .LBB0_674
	s_bitcmp1_b32 s22, 0
	s_cselect_b32 s22, 0xac00, 0
	s_add_i32 s22, s22, 0
	v_add_u32_e32 v14, s22, v223
	v_add_u32_e32 v14, v14, v204
	ds_read_b128 v[168:171], v14
	ds_read_b128 v[172:175], v14 offset:32
	ds_read_b128 v[176:179], v14 offset:64
	ds_read_b128 v[180:183], v14 offset:96
	ds_read_b128 v[184:187], v14 offset:128
	ds_read_b128 v[188:191], v14 offset:160
	ds_read_b128 v[192:195], v14 offset:192
	ds_read_b128 v[196:199], v14 offset:224
	buffer_load_dwordx4 v[10:13], v220, s[12:15], s6 offen
	buffer_load_dwordx4 v[160:163], v240, s[12:15], s6 offen
	buffer_load_dwordx4 v[164:167], v241, s[12:15], s6 offen
	s_add_i32 s60, s5, 0xff800000
	buffer_load_dwordx4 v[6:9], v221, s[16:19], s60 offen
	buffer_load_dwordx4 v[2:5], v221, s[16:19], s5 offen
	v_xor_b32_e32 v80, 0x80000000, v1
	v_mov_b32_e32 v81, v80
	v_mov_b64_e32 v[96:97], v[80:81]
	v_mov_b64_e32 v[98:99], v[80:81]
	v_mov_b64_e32 v[100:101], v[80:81]
	v_mov_b64_e32 v[102:103], v[80:81]
	v_mov_b64_e32 v[104:105], v[80:81]
	v_mov_b64_e32 v[106:107], v[80:81]
	v_mov_b64_e32 v[108:109], v[80:81]
	v_mov_b64_e32 v[110:111], v[80:81]
	s_waitcnt lgkmcnt(7)
	s_nop 0
	s_setprio 1
	v_mfma_f32_32x32x16_bf16 v[96:111], v[168:171], v[112:115], v[96:111]
	s_waitcnt lgkmcnt(6)
	v_mfma_f32_32x32x16_bf16 v[96:111], v[172:175], v[116:119], v[96:111]
	s_waitcnt lgkmcnt(5)
	v_mfma_f32_32x32x16_bf16 v[96:111], v[176:179], v[120:123], v[96:111]
	s_waitcnt lgkmcnt(4)
	v_mfma_f32_32x32x16_bf16 v[96:111], v[180:183], v[124:127], v[96:111]
	ds_read_b128 v[82:85], v14 offset:256
	ds_read_b128 v[86:89], v14 offset:288
	ds_read_b128 v[90:93], v14 offset:320
	ds_read_b128 v[168:171], v14 offset:352
	s_waitcnt lgkmcnt(7)
	v_mfma_f32_32x32x16_bf16 v[96:111], v[184:187], v[128:131], v[96:111]
	s_waitcnt lgkmcnt(6)
	v_mfma_f32_32x32x16_bf16 v[96:111], v[188:191], v[132:135], v[96:111]
	s_waitcnt lgkmcnt(5)
	v_mfma_f32_32x32x16_bf16 v[96:111], v[192:195], v[136:139], v[96:111]
	s_waitcnt lgkmcnt(4)
	v_mfma_f32_32x32x16_bf16 v[96:111], v[196:199], v[140:143], v[96:111]
	s_waitcnt lgkmcnt(3)
	v_mfma_f32_32x32x16_bf16 v[96:111], v[82:85], v[148:151], v[96:111]
	s_waitcnt lgkmcnt(2)
	v_mfma_f32_32x32x16_bf16 v[96:111], v[86:89], v[156:159], v[96:111]
	s_waitcnt lgkmcnt(1)
	v_mfma_f32_32x32x16_bf16 v[96:111], v[90:93], v[144:147], v[96:111]
	s_waitcnt lgkmcnt(0)
	v_mfma_f32_32x32x16_bf16 v[96:111], v[168:171], v[152:155], v[96:111]
	s_setprio 0
	ds_read_b128 v[196:199], v14 offset:12800
	ds_read_b128 v[192:195], v14 offset:12832
	ds_read_b128 v[188:191], v14 offset:12864
	ds_read_b128 v[184:187], v14 offset:12896
	ds_read_b128 v[180:183], v14 offset:12928
	ds_read_b128 v[176:179], v14 offset:12960
	ds_read_b128 v[172:175], v14 offset:12992
	ds_read_b128 v[168:171], v14 offset:13024
	s_nop 3
	v_max3_f32 v15, v96, v97, v98
	v_max3_f32 v81, v99, v100, v101
	v_max3_f32 v82, v102, v103, v104
	v_max3_f32 v83, v105, v106, v107
	v_max3_f32 v84, v108, v109, v110
	v_max3_f32 v15, v15, v81, v111
	v_max3_f32 v15, v15, v82, v83
	v_max_f32_e32 v15, v15, v84
	v_mov_b32_e32 v81, v15
	s_nop 1
	v_permlane32_swap_b32_e32 v81, v15
	v_max_f32_e32 v15, v15, v81
	v_cmp_lt_f32_e32 vcc, s47, v15
	s_cbranch_vccz .LBB0_671
	v_max_f32_e32 v15, v15, v15
	v_max_f32_e32 v80, 0, v15
	v_exp_f32_e64 v82, -v80
	v_add_f32_e32 v1, v1, v80
	v_pk_add_f32 v[96:97], v[96:97], v[80:81] op_sel_hi:[1,0] neg_lo:[0,1] neg_hi:[0,1]
	v_pk_add_f32 v[98:99], v[98:99], v[80:81] op_sel_hi:[1,0] neg_lo:[0,1] neg_hi:[0,1]
	v_pk_mul_f32 v[78:79], v[78:79], v[82:83] op_sel_hi:[1,0]
	v_pk_mul_f32 v[76:77], v[76:77], v[82:83] op_sel_hi:[1,0]
	v_pk_mul_f32 v[74:75], v[74:75], v[82:83] op_sel_hi:[1,0]
	v_pk_mul_f32 v[72:73], v[72:73], v[82:83] op_sel_hi:[1,0]
	v_pk_mul_f32 v[70:71], v[70:71], v[82:83] op_sel_hi:[1,0]
	v_pk_mul_f32 v[68:69], v[68:69], v[82:83] op_sel_hi:[1,0]
	v_pk_mul_f32 v[66:67], v[66:67], v[82:83] op_sel_hi:[1,0]
	v_pk_mul_f32 v[64:65], v[64:65], v[82:83] op_sel_hi:[1,0]
	v_pk_mul_f32 v[62:63], v[62:63], v[82:83] op_sel_hi:[1,0]
	v_pk_mul_f32 v[60:61], v[60:61], v[82:83] op_sel_hi:[1,0]
	v_pk_mul_f32 v[58:59], v[58:59], v[82:83] op_sel_hi:[1,0]
	v_pk_mul_f32 v[56:57], v[56:57], v[82:83] op_sel_hi:[1,0]
	v_pk_mul_f32 v[54:55], v[54:55], v[82:83] op_sel_hi:[1,0]
	v_pk_mul_f32 v[52:53], v[52:53], v[82:83] op_sel_hi:[1,0]
	v_pk_mul_f32 v[50:51], v[50:51], v[82:83] op_sel_hi:[1,0]
	v_pk_mul_f32 v[48:49], v[48:49], v[82:83] op_sel_hi:[1,0]
	v_pk_mul_f32 v[46:47], v[46:47], v[82:83] op_sel_hi:[1,0]
	v_pk_mul_f32 v[44:45], v[44:45], v[82:83] op_sel_hi:[1,0]
	v_pk_mul_f32 v[42:43], v[42:43], v[82:83] op_sel_hi:[1,0]
	v_pk_mul_f32 v[40:41], v[40:41], v[82:83] op_sel_hi:[1,0]
	v_pk_mul_f32 v[38:39], v[38:39], v[82:83] op_sel_hi:[1,0]
	v_pk_mul_f32 v[36:37], v[36:37], v[82:83] op_sel_hi:[1,0]
	v_pk_mul_f32 v[34:35], v[34:35], v[82:83] op_sel_hi:[1,0]
	v_pk_mul_f32 v[32:33], v[32:33], v[82:83] op_sel_hi:[1,0]
	v_pk_mul_f32 v[30:31], v[30:31], v[82:83] op_sel_hi:[1,0]
	v_pk_mul_f32 v[28:29], v[28:29], v[82:83] op_sel_hi:[1,0]
	v_pk_mul_f32 v[26:27], v[26:27], v[82:83] op_sel_hi:[1,0]
	v_pk_mul_f32 v[24:25], v[24:25], v[82:83] op_sel_hi:[1,0]
	v_pk_mul_f32 v[22:23], v[22:23], v[82:83] op_sel_hi:[1,0]
	v_pk_mul_f32 v[20:21], v[20:21], v[82:83] op_sel_hi:[1,0]
	v_pk_mul_f32 v[18:19], v[18:19], v[82:83] op_sel_hi:[1,0]
	v_pk_mul_f32 v[16:17], v[16:17], v[82:83] op_sel_hi:[1,0]
	v_pk_add_f32 v[100:101], v[100:101], v[80:81] op_sel_hi:[1,0] neg_lo:[0,1] neg_hi:[0,1]
	v_pk_add_f32 v[102:103], v[102:103], v[80:81] op_sel_hi:[1,0] neg_lo:[0,1] neg_hi:[0,1]
	v_pk_add_f32 v[104:105], v[104:105], v[80:81] op_sel_hi:[1,0] neg_lo:[0,1] neg_hi:[0,1]
	v_pk_add_f32 v[106:107], v[106:107], v[80:81] op_sel_hi:[1,0] neg_lo:[0,1] neg_hi:[0,1]
	v_pk_add_f32 v[108:109], v[108:109], v[80:81] op_sel_hi:[1,0] neg_lo:[0,1] neg_hi:[0,1]
	v_pk_add_f32 v[110:111], v[110:111], v[80:81] op_sel_hi:[1,0] neg_lo:[0,1] neg_hi:[0,1]
	v_mul_f32_e32 v216, v216, v82
	v_xor_b32_e32 v80, 0x80000000, v1

; #define LAS __attribute__((address_space(3)))
; __device__ __forceinline__ unsigned pk2(float lo, float hi) { return pg8::cvt_pk_bf16(lo, hi); }
; #define AT_LSTORE(buf_) do { AT_LSTORE_K(buf_); AT_LSTORE_V(buf_); } while (0)
; template <int MODE> __device__ __forceinline__ void attn_phase(LAS unsigned char* lds, const bf16_t* Q, const bf16_t* KF, const bf16_t* VT, bf16_t* O, const int* positions, const float* gq, int G, int bid) {
;     ...
;                     __builtin_amdgcn_sched_barrier(0);
; #pragma unroll
;                     for (int ks = 0; ks < 2; ++ks)
; #pragma unroll
;                         for (int db = 0; db < 4; ++db) o[db] = __builtin_amdgcn_mfma_f32_32x32x16_bf16(va[ks * 4 + db], pb[ks], o[db], 0, 0, 0);
;                     float ps1 = 0.f;
; #pragma unroll
;                     for (int i = 0; i < 16; ++i) { s1[i] = __builtin_amdgcn_exp2f(s1[i]); ps1 += s1[i]; }
; #pragma unroll
;                     for (int g = 0; g < 8; ++g) { __builtin_amdgcn_sched_group_barrier(0x008, 1, 0); __builtin_amdgcn_sched_group_barrier(0x002, 4, 0); }
;                     __builtin_amdgcn_sched_barrier(0);
;                     lsum += ps1;
; #pragma unroll
;                     for (int ks = 0; ks < 2; ++ks)
; #pragma unroll
;                         for (int db = 0; db < 4; ++db) va[ks * 4 + db] = *(const LAS bf16x8*)(vb + (32 * db + lq) * AT_VP + (16 * (ks + 2) + 8 * hi) * 2);
;                     if (more && MODE < 3) AT_LSTORE((kt + 1) & 1);
;                     __builtin_amdgcn_sched_barrier(0);
; #pragma unroll
;                     for (int ks = 0; ks < 2; ++ks)
; #pragma unroll
;                         for (int q = 0; q < 4; ++q) { const unsigned pk = pk2(s1[8 * ks + 2 * q], s1[8 * ks + 2 * q + 1]); pb[ks][2 * q] = (short)(pk & 0xffff); pb[ks][2 * q + 1] = (short)(pk >> 16); }
;                     __builtin_amdgcn_sched_barrier(0);
; #pragma unroll
;                     for (int ks = 0; ks < 2; ++ks)
; #pragma unroll
;                         for (int db = 0; db < 4; ++db) o[db] = __builtin_amdgcn_mfma_f32_32x32x16_bf16(va[ks * 4 + db], pb[ks], o[db], 0, 0, 0);
.LBB0_673:
	v_cvt_pk_bf16_f32 v246, v196, v197
	v_cvt_pk_bf16_f32 v247, v194, v195
	v_cvt_pk_bf16_f32 v248, v192, v193
	v_cvt_pk_bf16_f32 v249, v198, v199
	v_cvt_pk_bf16_f32 v186, v186, v187
	v_cvt_pk_bf16_f32 v187, v190, v191
	v_cvt_pk_bf16_f32 v188, v188, v189
	v_cvt_pk_bf16_f32 v189, v184, v185
	s_nop 0
	s_waitcnt lgkmcnt(7)
	v_mfma_f32_32x32x16_bf16 v[64:79], v[180:183], v[246:249], v[64:79]
	v_exp_f32_e32 v180, v80
	v_exp_f32_e32 v181, v81
	v_exp_f32_e32 v182, v82
	v_exp_f32_e32 v183, v83
	v_add_f32_e32 v15, 0, v180
	v_add_f32_e32 v15, v181, v15
	v_add_f32_e32 v15, v182, v15
	v_add_f32_e32 v15, v183, v15
	s_waitcnt lgkmcnt(5)
	v_mfma_f32_32x32x16_bf16 v[48:63], v[176:179], v[246:249], v[48:63]
	v_exp_f32_e32 v176, v84
	v_exp_f32_e32 v177, v85
	v_exp_f32_e32 v178, v86
	v_exp_f32_e32 v179, v87
	v_add_f32_e32 v15, v176, v15
	v_add_f32_e32 v15, v177, v15
	v_add_f32_e32 v15, v178, v15
	v_add_f32_e32 v15, v179, v15
	s_waitcnt lgkmcnt(3)
	v_mfma_f32_32x32x16_bf16 v[32:47], v[172:175], v[246:249], v[32:47]
	v_exp_f32_e32 v172, v88
	v_exp_f32_e32 v173, v89
	v_exp_f32_e32 v174, v90
	v_exp_f32_e32 v175, v91
	v_add_f32_e32 v15, v172, v15
	v_add_f32_e32 v15, v173, v15
	v_add_f32_e32 v15, v174, v15
	v_add_f32_e32 v15, v175, v15
	s_waitcnt lgkmcnt(1)
	v_mfma_f32_32x32x16_bf16 v[16:31], v[168:171], v[246:249], v[16:31]
	v_exp_f32_e32 v184, v92
	v_exp_f32_e32 v185, v93
	v_exp_f32_e32 v190, v94
	v_add_f32_e32 v15, v184, v15
	v_add_f32_e32 v15, v185, v15
	v_add_f32_e32 v217, v190, v15
	v_mfma_f32_32x32x16_bf16 v[64:79], v[100:103], v[186:189], v[64:79]
	v_exp_f32_e32 v15, v95
	v_mfma_f32_32x32x16_bf16 v[48:63], v[104:107], v[186:189], v[48:63]
	v_mfma_f32_32x32x16_bf16 v[32:47], v[108:111], v[186:189], v[32:47]
	s_waitcnt lgkmcnt(0)
	v_mfma_f32_32x32x16_bf16 v[16:31], v[96:99], v[186:189], v[16:31]
	s_bitcmp1_b32 s7, 0
	s_cselect_b32 s22, 0xac00, 0
	ds_read_b128 v[80:83], v245 offset:25664
	ds_read_b128 v[84:87], v245 offset:25696
	ds_read_b128 v[88:91], v245 offset:30272
	ds_read_b128 v[92:95], v245 offset:30304
	ds_read_b128 v[96:99], v245 offset:34880
	ds_read_b128 v[100:103], v245 offset:34912
	ds_read_b128 v[104:107], v245 offset:39488
	ds_read_b128 v[108:111], v245 offset:39520
	s_add_i32 s22, s22, 0
	v_pk_add_f32 v[168:169], v[14:15], v[216:217]
	v_add_u32_e32 v14, s22, v200
	s_waitcnt vmcnt(4)
	ds_write_b128 v14, v[10:13]
	s_waitcnt vmcnt(3)
	ds_write_b128 v14, v[160:163] offset:128
	s_waitcnt vmcnt(2)
	ds_write_b128 v14, v[164:167] offset:256
	v_add_u32_e32 v14, s22, v222
	v_add_f32_e32 v216, v168, v169
	v_add_u32_e32 v168, 0x6000, v14
	v_add_u32_e32 v14, 0x8800, v14
	s_waitcnt vmcnt(1)
	ds_write2_b64 v168, v[6:7], v[8:9] offset0:128 offset1:130
	s_waitcnt vmcnt(0)
	ds_write2_b64 v14, v[2:3], v[4:5] offset1:2
	v_cvt_pk_bf16_f32 v168, v180, v181
	v_cvt_pk_bf16_f32 v169, v182, v183
	v_cvt_pk_bf16_f32 v170, v176, v177
	v_cvt_pk_bf16_f32 v171, v178, v179
	v_cvt_pk_bf16_f32 v172, v172, v173
	v_cvt_pk_bf16_f32 v173, v174, v175
	v_cvt_pk_bf16_f32 v174, v184, v185
	v_cvt_pk_bf16_f32 v175, v190, v15
	s_waitcnt lgkmcnt(12)
	s_setprio 1
	v_mfma_f32_32x32x16_bf16 v[64:79], v[80:83], v[168:171], v[64:79]
	s_waitcnt lgkmcnt(10)
	v_mfma_f32_32x32x16_bf16 v[48:63], v[88:91], v[168:171], v[48:63]
	s_waitcnt lgkmcnt(8)
	v_mfma_f32_32x32x16_bf16 v[32:47], v[96:99], v[168:171], v[32:47]
	s_waitcnt lgkmcnt(6)
	v_mfma_f32_32x32x16_bf16 v[16:31], v[104:107], v[168:171], v[16:31]
	v_mfma_f32_32x32x16_bf16 v[64:79], v[84:87], v[172:175], v[64:79]
	v_mfma_f32_32x32x16_bf16 v[48:63], v[92:95], v[172:175], v[48:63]
	v_mfma_f32_32x32x16_bf16 v[32:47], v[100:103], v[172:175], v[32:47]
	s_waitcnt lgkmcnt(5)
	v_mfma_f32_32x32x16_bf16 v[16:31], v[108:111], v[172:175], v[16:31]
	s_setprio 0

; #define AT_LSTORE(buf_) do { AT_LSTORE_K(buf_); AT_LSTORE_V(buf_); } while (0)
; template <int MODE> __device__ __forceinline__ void attn_phase(LAS unsigned char* lds, const bf16_t* Q, const bf16_t* KF, const bf16_t* VT, bf16_t* O, const int* positions, const float* gq, int G, int bid) {
;     ...
;                 if (more && MODE < 3 && kt > my_last) AT_LSTORE((kt + 1) & 1);
.Lattn_idle:
	buffer_load_dwordx4 v[10:13], v220, s[12:15], s6 offen
	buffer_load_dwordx4 v[160:163], v240, s[12:15], s6 offen
	buffer_load_dwordx4 v[164:167], v241, s[12:15], s6 offen
	s_add_i32 s60, s5, 0xff800000
	buffer_load_dwordx4 v[6:9], v221, s[16:19], s60 offen
	buffer_load_dwordx4 v[2:5], v221, s[16:19], s5 offen
	s_and_saveexec_b64 s[44:45], vcc
	s_branch .LBB0_674
